# RG-LRU gate matmuls: LDS fragment reads double-buffered ahead of the MFMAs (was read, wait, MFMA per step)
# baseline (speedup 1.0000x reference)
; #define LAS __attribute__((address_space(3)))
; __device__ __forceinline__ float fast_exp2(float x) { return __builtin_amdgcn_exp2f(x); }
; __device__ __forceinline__ float sigmoidf_(float x) { return fast_rcp(1.0f + fast_exp2(-x * LOG2E)); }
; __device__ __forceinline__ int crow(int r, int hi) { return (r & 3) + 8 * (r >> 2) + 4 * hi; }
; __device__ __forceinline__ void rglru_unit(const Params& P, int l, int unit, LAS unsigned char* lds, bool dry = false) {
;     ...
;         bf16_t* gp = proj + O_GR + (rowb + t0 + 16 * ss) * XP + 128 * n + 64 * j + sc;
;         unsigned short gq[16];
; #pragma unroll
;         for (int k = 0; k < 16; ++k) gq[k] = gp[(size_t)k * XP];
;         __syncthreads();
;         f32x16 accr = {}, acci = {};
; #pragma unroll
;         for (int s = 0; s < 8; ++s) { const bf16x8 a = *(const LAS bf16x8*)(xc + (32 * tb + r32) * 272 + (16 * s + 8 * hi) * 2);
;             const bf16x8 wr_ = *(const LAS bf16x8*)(WB + (32 * cb + r32) * 272 + (16 * s + 8 * hi) * 2), wi_ = *(const LAS bf16x8*)(WB + (64 + 32 * cb + r32) * 272 + (16 * s + 8 * hi) * 2);
;             accr = __builtin_amdgcn_mfma_f32_32x32x16_bf16(a, wr_, accr, 0, 0, 0); acci = __builtin_amdgcn_mfma_f32_32x32x16_bf16(a, wi_, acci, 0, 0, 0); }
; #pragma unroll
;         for (int r = 0; r < 16; ++r) { const int tok = 32 * tb + crow(r, hi);
;             const float rr = sigmoidf_(accr[r] + br), ii = sigmoidf_(acci[r] + bi);
;             const float la = -rr * sp8; const float a = fast_exp2(la * LOG2E);
;             const float x2 = 2.0f * la;
;             const float em = -x2 * (1.0f + x2 * (0.5f + x2 * (0.16666667f + x2 * (0.041666668f + x2 * (0.0083333338f + x2 * 0.0013888889f)))));
;             const float mult = __builtin_sqrtf(fmaxf(em, 0.f));
;             const float xcv = bf2f(*(const LAS unsigned short*)(xc + tok * 272 + dch * 2));
;             Ab[tok * 64 + 32 * cb + r32] = a; Ub[tok * 64 + 32 * cb + r32] = mult * ii * xcv; }
.LBB0_367:
	v_lshl_add_u64 v[2:3], v[108:109], 0, s[22:23]
	v_add_co_u32_e32 v126, vcc, 0xae00000, v2
	s_add_u32 s22, s22, 0x40000
	s_nop 0
	v_addc_co_u32_e32 v127, vcc, 0, v3, vcc
	v_add_co_u32_e32 v124, vcc, 0xae01000, v2
	s_addc_u32 s23, s23, 0
	s_nop 0
	v_addc_co_u32_e32 v125, vcc, 0, v3, vcc
	v_add_co_u32_e32 v122, vcc, 0xae02000, v2
	s_cmp_lg_u32 s22, 0x400000
	s_nop 0
	v_addc_co_u32_e32 v123, vcc, 0, v3, vcc
	v_add_co_u32_e32 v120, vcc, 0xae03000, v2
	v_add_u32_e32 v110, 0x80, v110
	s_nop 0
	v_addc_co_u32_e32 v121, vcc, 0, v3, vcc
	v_add_co_u32_e32 v118, vcc, 0xae04000, v2
	global_load_ushort v207, v[126:127], off
	global_load_ushort v206, v[126:127], off offset:2048
	global_load_ushort v205, v[124:125], off
	global_load_ushort v204, v[124:125], off offset:2048
	global_load_ushort v203, v[122:123], off
	global_load_ushort v202, v[122:123], off offset:2048
	global_load_ushort v201, v[120:121], off
	global_load_ushort v200, v[120:121], off offset:2048
	v_addc_co_u32_e32 v119, vcc, 0, v3, vcc
	v_add_co_u32_e32 v116, vcc, 0xae05000, v2
	s_nop 1
	v_addc_co_u32_e32 v117, vcc, 0, v3, vcc
	v_add_co_u32_e32 v114, vcc, 0xae06000, v2
	s_nop 1
	v_addc_co_u32_e32 v115, vcc, 0, v3, vcc
	v_add_co_u32_e32 v112, vcc, 0xae07000, v2
	s_nop 1
	v_addc_co_u32_e32 v113, vcc, 0, v3, vcc
	global_load_ushort v199, v[118:119], off
	global_load_ushort v198, v[118:119], off offset:2048
	global_load_ushort v197, v[116:117], off
	global_load_ushort v196, v[116:117], off offset:2048
	global_load_ushort v195, v[114:115], off
	global_load_ushort v194, v[114:115], off offset:2048
	global_load_ushort v111, v[112:113], off
	global_load_ushort v1, v[112:113], off offset:2048
	s_waitcnt lgkmcnt(0)
	s_barrier
	ds_read_b128 v[208:211], v190
	ds_read_b128 v[212:215], v191
	ds_read_b128 v[226:229], v192
	ds_read_b128 v[232:235], v190 offset:32
	ds_read_b128 v[236:239], v191 offset:32
	ds_read_b128 v[240:243], v192 offset:32
	s_waitcnt lgkmcnt(3)
	v_mfma_f32_32x32x16_bf16 v[18:33], v[208:211], v[212:215], 0
	v_mfma_f32_32x32x16_bf16 v[2:17], v[208:211], v[226:229], 0
	ds_read_b128 v[208:211], v190 offset:64
	ds_read_b128 v[212:215], v191 offset:64
	ds_read_b128 v[226:229], v192 offset:64
	s_waitcnt lgkmcnt(3)
	v_mfma_f32_32x32x16_bf16 v[18:33], v[232:235], v[236:239], v[18:33]
	v_mfma_f32_32x32x16_bf16 v[2:17], v[232:235], v[240:243], v[2:17]
	ds_read_b128 v[232:235], v190 offset:96
	ds_read_b128 v[236:239], v191 offset:96
	ds_read_b128 v[240:243], v192 offset:96
	s_waitcnt lgkmcnt(3)
	v_mfma_f32_32x32x16_bf16 v[18:33], v[208:211], v[212:215], v[18:33]
	v_mfma_f32_32x32x16_bf16 v[2:17], v[208:211], v[226:229], v[2:17]
	ds_read_b128 v[208:211], v190 offset:128
	ds_read_b128 v[212:215], v191 offset:128
	ds_read_b128 v[226:229], v192 offset:128
	s_waitcnt lgkmcnt(3)
	v_mfma_f32_32x32x16_bf16 v[18:33], v[232:235], v[236:239], v[18:33]
	v_mfma_f32_32x32x16_bf16 v[2:17], v[232:235], v[240:243], v[2:17]
	ds_read_b128 v[232:235], v190 offset:160
	ds_read_b128 v[236:239], v191 offset:160
	ds_read_b128 v[240:243], v192 offset:160
	s_waitcnt lgkmcnt(3)
	v_mfma_f32_32x32x16_bf16 v[18:33], v[208:211], v[212:215], v[18:33]
	v_mfma_f32_32x32x16_bf16 v[2:17], v[208:211], v[226:229], v[2:17]
	ds_read_b128 v[208:211], v190 offset:192
	ds_read_b128 v[212:215], v191 offset:192
	ds_read_b128 v[226:229], v192 offset:192
	s_waitcnt lgkmcnt(3)
	v_mfma_f32_32x32x16_bf16 v[18:33], v[232:235], v[236:239], v[18:33]
	v_mfma_f32_32x32x16_bf16 v[2:17], v[232:235], v[240:243], v[2:17]
	ds_read_b128 v[232:235], v190 offset:224
	ds_read_b128 v[236:239], v191 offset:224
	ds_read_b128 v[240:243], v192 offset:224
	s_waitcnt lgkmcnt(3)
	v_mfma_f32_32x32x16_bf16 v[18:33], v[208:211], v[212:215], v[18:33]
	v_mfma_f32_32x32x16_bf16 v[2:17], v[208:211], v[226:229], v[2:17]
	s_waitcnt lgkmcnt(0)
	v_mfma_f32_32x32x16_bf16 v[18:33], v[232:235], v[236:239], v[18:33]
	v_mfma_f32_32x32x16_bf16 v[2:17], v[232:235], v[240:243], v[2:17]
	s_nop 10
	v_add_f32_e32 v18, v128, v18
	v_mul_f32_e32 v18, 0xbfb8aa3b, v18
	v_exp_f32_e32 v18, v18
	v_add_f32_e32 v19, v128, v19
	v_mul_f32_e32 v19, 0xbfb8aa3b, v19
	v_exp_f32_e32 v19, v19
	v_add_f32_e32 v18, 1.0, v18
	v_rcp_f32_e64 v18, -v18
	v_add_f32_e32 v2, v129, v2
	v_mul_f32_e32 v2, 0xbfb8aa3b, v2
	v_exp_f32_e32 v2, v2
	v_mul_f32_e32 v18, v130, v18
	v_add_f32_e32 v86, v18, v18
	v_fmamk_f32 v87, v86, 0x3ab60b61, v218
	v_fmaak_f32 v87, v86, v87, 0x3d2aaaab
	v_fmaak_f32 v87, v86, v87, 0x3e2aaaab
	v_fma_f32 v87, v86, v87, 0.5
	v_fma_f32 v87, v86, v87, 1.0
	v_mul_f32_e64 v86, v87, -v86
	v_max_f32_e32 v86, 0, v86
	v_mul_f32_e32 v18, 0x3fb8aa3b, v18
	v_exp_f32_e32 v18, v18
	v_add_f32_e32 v2, 1.0, v2
	v_rcp_f32_e32 v2, v2
	v_add_f32_e32 v3, v129, v3
	v_mul_f32_e32 v3, 0xbfb8aa3b, v3
	v_exp_f32_e32 v3, v3
	v_add_f32_e32 v4, v129, v4
	v_mul_f32_e32 v4, 0xbfb8aa3b, v4
	v_exp_f32_e32 v4, v4
	v_sqrt_f32_e32 v86, v86
	ds_read_u16 v87, v193
	ds_read_u16 v88, v193 offset:272
	ds_read_u16 v182, v193 offset:544
	ds_read_u16 v183, v193 offset:816
	ds_read_u16 v184, v193 offset:2176
	ds_read_u16 v185, v193 offset:2448
	ds_read_u16 v208, v193 offset:2720
	ds_read_u16 v209, v193 offset:2992
	ds_write_b32 v134, v18 offset:34816
	v_add_f32_e32 v18, 1.0, v19
	v_rcp_f32_e64 v18, -v18
	s_waitcnt lgkmcnt(8)
	v_lshlrev_b32_e32 v87, 16, v87
	v_mul_f32_e32 v2, v2, v86
	v_mul_f32_e32 v2, v2, v87
	ds_write_b32 v135, v2
	v_add_f32_e32 v2, 1.0, v3
	v_mul_f32_e32 v3, v130, v18
	v_add_f32_e32 v18, v3, v3
	v_fmamk_f32 v19, v18, 0x3ab60b61, v218
	v_fmaak_f32 v19, v18, v19, 0x3d2aaaab
	v_fmaak_f32 v19, v18, v19, 0x3e2aaaab
	v_fma_f32 v19, v18, v19, 0.5
	v_fma_f32 v19, v18, v19, 1.0
	v_mul_f32_e64 v18, v19, -v18
	v_max_f32_e32 v18, 0, v18
	v_mul_f32_e32 v3, 0x3fb8aa3b, v3
	v_exp_f32_e32 v3, v3
	v_rcp_f32_e32 v2, v2
	ds_write_b32 v136, v3 offset:34816
	s_nop 0
	s_nop 1
	v_sqrt_f32_e32 v18, v18
	v_add_f32_e32 v19, v128, v20
	v_mul_f32_e32 v19, 0xbfb8aa3b, v19
	v_exp_f32_e32 v19, v19
	s_waitcnt lgkmcnt(9)
; #define LAS __attribute__((address_space(3)))
; __device__ __forceinline__ float fast_exp2(float x) { return __builtin_amdgcn_exp2f(x); }
; __device__ __forceinline__ float sigmoidf_(float x) { return fast_rcp(1.0f + fast_exp2(-x * LOG2E)); }
; __device__ __forceinline__ int crow(int r, int hi) { return (r & 3) + 8 * (r >> 2) + 4 * hi; }
; __device__ __forceinline__ void rglru_unit(const Params& P, int l, int unit, LAS unsigned char* lds, bool dry = false) {
;     ...
;         for (int r = 0; r < 16; ++r) { const int tok = 32 * tb + crow(r, hi);
;             const float rr = sigmoidf_(accr[r] + br), ii = sigmoidf_(acci[r] + bi);
;             const float la = -rr * sp8; const float a = fast_exp2(la * LOG2E);
;             const float x2 = 2.0f * la;
;             const float em = -x2 * (1.0f + x2 * (0.5f + x2 * (0.16666667f + x2 * (0.041666668f + x2 * (0.0083333338f + x2 * 0.0013888889f)))));
;             const float mult = __builtin_sqrtf(fmaxf(em, 0.f));
;             const float xcv = bf2f(*(const LAS unsigned short*)(xc + tok * 272 + dch * 2));
;             Ab[tok * 64 + 32 * cb + r32] = a; Ub[tok * 64 + 32 * cb + r32] = mult * ii * xcv; }
	v_lshlrev_b32_e32 v20, 16, v88
	v_mul_f32_e32 v2, v2, v18
	v_mul_f32_e32 v2, v2, v20
	v_add_f32_e32 v3, 1.0, v19
	v_rcp_f32_e64 v3, -v3
	ds_write_b32 v137, v2
	v_add_f32_e32 v2, 1.0, v4
	v_rcp_f32_e32 v2, v2
	v_mul_f32_e32 v3, v130, v3
	v_add_f32_e32 v4, v3, v3
	v_fmamk_f32 v18, v4, 0x3ab60b61, v218
	v_fmaak_f32 v18, v4, v18, 0x3d2aaaab
	v_fmaak_f32 v18, v4, v18, 0x3e2aaaab
	v_fma_f32 v18, v4, v18, 0.5
	v_fma_f32 v18, v4, v18, 1.0
	v_mul_f32_e64 v4, v18, -v4
	v_max_f32_e32 v4, 0, v4
	v_mul_f32_e32 v3, 0x3fb8aa3b, v3
	v_exp_f32_e32 v3, v3
	ds_write_b32 v138, v3 offset:34816
	s_nop 0
	s_waitcnt lgkmcnt(10)
	v_lshlrev_b32_e32 v19, 16, v182
	v_sqrt_f32_e32 v4, v4
	v_add_f32_e32 v18, v128, v21
	v_mul_f32_e32 v18, 0xbfb8aa3b, v18
	v_exp_f32_e32 v18, v18
	v_mul_f32_e32 v2, v2, v4
	v_add_f32_e32 v4, v129, v5
	v_mul_f32_e32 v4, 0xbfb8aa3b, v4
	v_add_f32_e32 v3, 1.0, v18
	v_rcp_f32_e64 v3, -v3
	v_exp_f32_e32 v4, v4
	v_mul_f32_e32 v2, v2, v19
	ds_write_b32 v139, v2
	v_mul_f32_e32 v3, v130, v3
	v_add_f32_e32 v2, 1.0, v4
	v_add_f32_e32 v4, v3, v3
	v_fmamk_f32 v5, v4, 0x3ab60b61, v218
	v_fmaak_f32 v5, v4, v5, 0x3d2aaaab
	v_fmaak_f32 v5, v4, v5, 0x3e2aaaab
	v_fma_f32 v5, v4, v5, 0.5
	v_fma_f32 v5, v4, v5, 1.0
	v_mul_f32_e64 v4, v5, -v4
	v_max_f32_e32 v4, 0, v4
	v_mul_f32_e32 v3, 0x3fb8aa3b, v3
	v_rcp_f32_e32 v2, v2
	v_exp_f32_e32 v3, v3
	ds_write_b32 v140, v3 offset:34816
	s_waitcnt lgkmcnt(11)
	v_lshlrev_b32_e32 v18, 16, v183
	v_sqrt_f32_e32 v4, v4
	v_add_f32_e32 v5, v128, v22
	v_mul_f32_e32 v5, 0xbfb8aa3b, v5
	v_exp_f32_e32 v5, v5
	v_mul_f32_e32 v2, v2, v4
	v_add_f32_e32 v4, v129, v6
	v_mul_f32_e32 v4, 0xbfb8aa3b, v4
	v_add_f32_e32 v3, 1.0, v5
	v_rcp_f32_e64 v3, -v3
	v_exp_f32_e32 v4, v4
	v_mul_f32_e32 v2, v2, v18
	ds_write_b32 v141, v2
	v_mul_f32_e32 v3, v130, v3
	v_add_f32_e32 v2, 1.0, v4
	v_add_f32_e32 v4, v3, v3
	v_fmamk_f32 v5, v4, 0x3ab60b61, v218
	v_fmaak_f32 v5, v4, v5, 0x3d2aaaab
	v_fmaak_f32 v5, v4, v5, 0x3e2aaaab
	v_fma_f32 v5, v4, v5, 0.5
	v_fma_f32 v5, v4, v5, 1.0
	v_mul_f32_e64 v4, v5, -v4
	v_max_f32_e32 v4, 0, v4
	v_mul_f32_e32 v3, 0x3fb8aa3b, v3
	v_rcp_f32_e32 v2, v2
	v_exp_f32_e32 v3, v3
	ds_write_b32 v142, v3 offset:34816
	s_waitcnt lgkmcnt(12)
	v_lshlrev_b32_e32 v6, 16, v184
	v_sqrt_f32_e32 v4, v4
	v_add_f32_e32 v5, v128, v23
	v_mul_f32_e32 v5, 0xbfb8aa3b, v5
	v_exp_f32_e32 v5, v5
	v_mul_f32_e32 v2, v2, v4
	v_add_f32_e32 v4, v129, v7
	v_mul_f32_e32 v4, 0xbfb8aa3b, v4
	v_add_f32_e32 v3, 1.0, v5
	v_rcp_f32_e64 v3, -v3
	v_exp_f32_e32 v4, v4
	v_mul_f32_e32 v2, v2, v6
	ds_write_b32 v143, v2
	v_mul_f32_e32 v3, v130, v3
	v_add_f32_e32 v2, 1.0, v4
	v_add_f32_e32 v4, v3, v3
	v_fmamk_f32 v5, v4, 0x3ab60b61, v218
	v_fmaak_f32 v5, v4, v5, 0x3d2aaaab
	v_fmaak_f32 v5, v4, v5, 0x3e2aaaab
	v_fma_f32 v5, v4, v5, 0.5
	v_fma_f32 v5, v4, v5, 1.0
	v_mul_f32_e64 v4, v5, -v4
	v_max_f32_e32 v4, 0, v4
	v_mul_f32_e32 v3, 0x3fb8aa3b, v3
	v_rcp_f32_e32 v2, v2
	v_exp_f32_e32 v3, v3
	ds_write_b32 v144, v3 offset:34816
	s_waitcnt lgkmcnt(13)
	v_lshlrev_b32_e32 v6, 16, v185
	v_sqrt_f32_e32 v4, v4
	v_add_f32_e32 v5, v128, v24
	v_mul_f32_e32 v5, 0xbfb8aa3b, v5
	v_exp_f32_e32 v5, v5
	v_mul_f32_e32 v2, v2, v4
	v_add_f32_e32 v4, v129, v8
	v_mul_f32_e32 v4, 0xbfb8aa3b, v4
	v_add_f32_e32 v3, 1.0, v5
	v_rcp_f32_e64 v3, -v3
	v_exp_f32_e32 v4, v4
	v_mul_f32_e32 v2, v2, v6
	ds_write_b32 v145, v2
	v_mul_f32_e32 v3, v130, v3
	v_add_f32_e32 v2, 1.0, v4
	v_add_f32_e32 v4, v3, v3
	v_fmamk_f32 v5, v4, 0x3ab60b61, v218
	v_fmaak_f32 v5, v4, v5, 0x3d2aaaab
	v_fmaak_f32 v5, v4, v5, 0x3e2aaaab
	v_fma_f32 v5, v4, v5, 0.5
	v_fma_f32 v5, v4, v5, 1.0
	v_mul_f32_e64 v4, v5, -v4
	v_max_f32_e32 v4, 0, v4
	v_mul_f32_e32 v3, 0x3fb8aa3b, v3
	v_rcp_f32_e32 v2, v2
	v_exp_f32_e32 v3, v3
	ds_write_b32 v146, v3 offset:34816
	s_waitcnt lgkmcnt(14)
	v_lshlrev_b32_e32 v6, 16, v208
	v_sqrt_f32_e32 v4, v4
	v_add_f32_e32 v5, v128, v25
	v_mul_f32_e32 v5, 0xbfb8aa3b, v5
	v_exp_f32_e32 v5, v5
	v_mul_f32_e32 v2, v2, v4
	v_add_f32_e32 v4, v129, v9
	v_mul_f32_e32 v4, 0xbfb8aa3b, v4
	v_add_f32_e32 v3, 1.0, v5
	v_rcp_f32_e64 v3, -v3
	v_exp_f32_e32 v4, v4
	v_mul_f32_e32 v2, v2, v6
	ds_write_b32 v147, v2
	v_mul_f32_e32 v3, v130, v3
	v_add_f32_e32 v2, 1.0, v4
	v_add_f32_e32 v4, v3, v3
	v_fmamk_f32 v5, v4, 0x3ab60b61, v218
	v_fmaak_f32 v5, v4, v5, 0x3d2aaaab
	v_fmaak_f32 v5, v4, v5, 0x3e2aaaab
	v_fma_f32 v5, v4, v5, 0.5
	v_fma_f32 v5, v4, v5, 1.0
	v_mul_f32_e64 v4, v5, -v4
	v_max_f32_e32 v4, 0, v4
	v_mul_f32_e32 v3, 0x3fb8aa3b, v3
	v_rcp_f32_e32 v2, v2
	v_exp_f32_e32 v3, v3
	ds_write_b32 v148, v3 offset:34816
	s_waitcnt lgkmcnt(14)
	v_lshlrev_b32_e32 v6, 16, v209
	v_sqrt_f32_e32 v4, v4
	v_add_f32_e32 v5, v128, v26
	v_mul_f32_e32 v5, 0xbfb8aa3b, v5
	v_exp_f32_e32 v5, v5
	v_mul_f32_e32 v2, v2, v4
	v_add_f32_e32 v4, v129, v10
	v_mul_f32_e32 v4, 0xbfb8aa3b, v4
	v_add_f32_e32 v3, 1.0, v5
	v_rcp_f32_e64 v3, -v3
	v_exp_f32_e32 v4, v4
	v_mul_f32_e32 v2, v2, v6
	ds_write_b32 v149, v2
	v_mul_f32_e32 v3, v130, v3
	v_add_f32_e32 v2, 1.0, v4
	v_add_f32_e32 v4, v3, v3
	v_fmamk_f32 v5, v4, 0x3ab60b61, v218
	v_fmaak_f32 v5, v4, v5, 0x3d2aaaab
	v_fmaak_f32 v5, v4, v5, 0x3e2aaaab
	v_fma_f32 v5, v4, v5, 0.5
	v_fma_f32 v5, v4, v5, 1.0
	v_mul_f32_e64 v4, v5, -v4
	v_max_f32_e32 v4, 0, v4
	v_mul_f32_e32 v3, 0x3fb8aa3b, v3
	v_rcp_f32_e32 v2, v2
	v_exp_f32_e32 v3, v3
	s_nop 0
	ds_read_u16 v6, v193 offset:4352
	ds_read_u16 v7, v193 offset:4624
	ds_read_u16 v8, v193 offset:4896
	ds_read_u16 v9, v193 offset:5168
	ds_read_u16 v10, v193 offset:6528
	ds_read_u16 v18, v193 offset:6800
	ds_read_u16 v19, v193 offset:7072
	ds_read_u16 v20, v193 offset:7344
	v_sqrt_f32_e32 v4, v4
	v_add_f32_e32 v5, v128, v27
	v_mul_f32_e32 v5, 0xbfb8aa3b, v5
	v_exp_f32_e32 v5, v5
	ds_write_b32 v150, v3 offset:34816
	v_mul_f32_e32 v2, v2, v4
	v_add_f32_e32 v4, v129, v11
	v_add_f32_e32 v3, 1.0, v5
	v_mul_f32_e32 v4, 0xbfb8aa3b, v4
	v_rcp_f32_e64 v3, -v3
	v_exp_f32_e32 v4, v4
	s_waitcnt lgkmcnt(8)
; #define LAS __attribute__((address_space(3)))
; __device__ __forceinline__ float fast_exp2(float x) { return __builtin_amdgcn_exp2f(x); }
; __device__ __forceinline__ float sigmoidf_(float x) { return fast_rcp(1.0f + fast_exp2(-x * LOG2E)); }
; __device__ __forceinline__ int crow(int r, int hi) { return (r & 3) + 8 * (r >> 2) + 4 * hi; }
; __device__ __forceinline__ void rglru_unit(const Params& P, int l, int unit, LAS unsigned char* lds, bool dry = false) {
;     ...
;         for (int r = 0; r < 16; ++r) { const int tok = 32 * tb + crow(r, hi);
;             const float rr = sigmoidf_(accr[r] + br), ii = sigmoidf_(acci[r] + bi);
;             const float la = -rr * sp8; const float a = fast_exp2(la * LOG2E);
;             const float x2 = 2.0f * la;
;             const float em = -x2 * (1.0f + x2 * (0.5f + x2 * (0.16666667f + x2 * (0.041666668f + x2 * (0.0083333338f + x2 * 0.0013888889f)))));
;             const float mult = __builtin_sqrtf(fmaxf(em, 0.f));
;             const float xcv = bf2f(*(const LAS unsigned short*)(xc + tok * 272 + dch * 2));
;             Ab[tok * 64 + 32 * cb + r32] = a; Ub[tok * 64 + 32 * cb + r32] = mult * ii * xcv; }
;         __syncthreads();
	v_lshlrev_b32_e32 v6, 16, v6
	v_mul_f32_e32 v2, v2, v6
	v_mul_f32_e32 v3, v130, v3
	ds_write_b32 v151, v2
	v_add_f32_e32 v2, 1.0, v4
	v_add_f32_e32 v4, v3, v3
	v_fmamk_f32 v5, v4, 0x3ab60b61, v218
	v_fmaak_f32 v5, v4, v5, 0x3d2aaaab
	v_fmaak_f32 v5, v4, v5, 0x3e2aaaab
	v_fma_f32 v5, v4, v5, 0.5
	v_fma_f32 v5, v4, v5, 1.0
	v_mul_f32_e64 v4, v5, -v4
	v_max_f32_e32 v4, 0, v4
	v_mul_f32_e32 v3, 0x3fb8aa3b, v3
	v_rcp_f32_e32 v2, v2
	v_exp_f32_e32 v3, v3
	ds_write_b32 v152, v3 offset:34816
	s_waitcnt lgkmcnt(9)
	v_lshlrev_b32_e32 v6, 16, v7
	v_sqrt_f32_e32 v4, v4
	v_add_f32_e32 v5, v128, v28
	v_mul_f32_e32 v5, 0xbfb8aa3b, v5
	v_exp_f32_e32 v5, v5
	v_mul_f32_e32 v2, v2, v4
	v_add_f32_e32 v4, v129, v12
	v_mul_f32_e32 v4, 0xbfb8aa3b, v4
	v_add_f32_e32 v3, 1.0, v5
	v_rcp_f32_e64 v3, -v3
	v_exp_f32_e32 v4, v4
	v_mul_f32_e32 v2, v2, v6
	ds_write_b32 v153, v2
	v_mul_f32_e32 v3, v130, v3
	v_add_f32_e32 v2, 1.0, v4
	v_add_f32_e32 v4, v3, v3
	v_fmamk_f32 v5, v4, 0x3ab60b61, v218
	v_fmaak_f32 v5, v4, v5, 0x3d2aaaab
	v_fmaak_f32 v5, v4, v5, 0x3e2aaaab
	v_fma_f32 v5, v4, v5, 0.5
	v_fma_f32 v5, v4, v5, 1.0
	v_mul_f32_e64 v4, v5, -v4
	v_max_f32_e32 v4, 0, v4
	v_mul_f32_e32 v3, 0x3fb8aa3b, v3
	v_rcp_f32_e32 v2, v2
	v_exp_f32_e32 v3, v3
	ds_write_b32 v154, v3 offset:34816
	s_waitcnt lgkmcnt(10)
	v_lshlrev_b32_e32 v6, 16, v8
	v_sqrt_f32_e32 v4, v4
	v_add_f32_e32 v5, v128, v29
	v_mul_f32_e32 v5, 0xbfb8aa3b, v5
	v_exp_f32_e32 v5, v5
	v_mul_f32_e32 v2, v2, v4
	v_add_f32_e32 v4, v129, v13
	v_mul_f32_e32 v4, 0xbfb8aa3b, v4
	v_add_f32_e32 v3, 1.0, v5
	v_rcp_f32_e64 v3, -v3
	v_exp_f32_e32 v4, v4
	v_mul_f32_e32 v2, v2, v6
	ds_write_b32 v155, v2
	v_mul_f32_e32 v3, v130, v3
	v_add_f32_e32 v2, 1.0, v4
	v_add_f32_e32 v4, v3, v3
	v_fmamk_f32 v5, v4, 0x3ab60b61, v218
	v_fmaak_f32 v5, v4, v5, 0x3d2aaaab
	v_fmaak_f32 v5, v4, v5, 0x3e2aaaab
	v_fma_f32 v5, v4, v5, 0.5
	v_fma_f32 v5, v4, v5, 1.0
	v_mul_f32_e64 v4, v5, -v4
	v_max_f32_e32 v4, 0, v4
	v_mul_f32_e32 v3, 0x3fb8aa3b, v3
	v_rcp_f32_e32 v2, v2
	v_exp_f32_e32 v3, v3
	ds_write_b32 v156, v3 offset:34816
	s_waitcnt lgkmcnt(11)
	v_lshlrev_b32_e32 v6, 16, v9
	v_sqrt_f32_e32 v4, v4
	v_add_f32_e32 v5, v128, v30
	v_mul_f32_e32 v5, 0xbfb8aa3b, v5
	v_exp_f32_e32 v5, v5
	v_mul_f32_e32 v2, v2, v4
	v_add_f32_e32 v4, v129, v14
	v_mul_f32_e32 v4, 0xbfb8aa3b, v4
	v_add_f32_e32 v3, 1.0, v5
	v_rcp_f32_e64 v3, -v3
	v_exp_f32_e32 v4, v4
	v_mul_f32_e32 v2, v2, v6
	ds_write_b32 v157, v2
	v_mul_f32_e32 v3, v130, v3
	v_add_f32_e32 v2, 1.0, v4
	v_add_f32_e32 v4, v3, v3
	v_fmamk_f32 v5, v4, 0x3ab60b61, v218
	v_fmaak_f32 v5, v4, v5, 0x3d2aaaab
	v_fmaak_f32 v5, v4, v5, 0x3e2aaaab
	v_fma_f32 v5, v4, v5, 0.5
	v_fma_f32 v5, v4, v5, 1.0
	v_mul_f32_e64 v4, v5, -v4
	v_max_f32_e32 v4, 0, v4
	v_mul_f32_e32 v3, 0x3fb8aa3b, v3
	v_rcp_f32_e32 v2, v2
	v_exp_f32_e32 v3, v3
	ds_write_b32 v158, v3 offset:34816
	s_waitcnt lgkmcnt(12)
	v_lshlrev_b32_e32 v6, 16, v10
	v_sqrt_f32_e32 v4, v4
	v_add_f32_e32 v5, v128, v31
	v_mul_f32_e32 v5, 0xbfb8aa3b, v5
	v_exp_f32_e32 v5, v5
	v_mul_f32_e32 v2, v2, v4
	v_add_f32_e32 v4, v129, v15
	v_mul_f32_e32 v4, 0xbfb8aa3b, v4
	v_add_f32_e32 v3, 1.0, v5
	v_rcp_f32_e64 v3, -v3
	v_exp_f32_e32 v4, v4
	v_mul_f32_e32 v2, v2, v6
	ds_write_b32 v159, v2
	v_mul_f32_e32 v3, v130, v3
	v_add_f32_e32 v2, 1.0, v4
	v_add_f32_e32 v4, v3, v3
	v_fmamk_f32 v5, v4, 0x3ab60b61, v218
	v_fmaak_f32 v5, v4, v5, 0x3d2aaaab
	v_fmaak_f32 v5, v4, v5, 0x3e2aaaab
	v_fma_f32 v5, v4, v5, 0.5
	v_fma_f32 v5, v4, v5, 1.0
	v_mul_f32_e64 v4, v5, -v4
	v_max_f32_e32 v4, 0, v4
	v_mul_f32_e32 v3, 0x3fb8aa3b, v3
	v_rcp_f32_e32 v2, v2
	v_exp_f32_e32 v3, v3
	ds_write_b32 v160, v3 offset:34816
	s_waitcnt lgkmcnt(13)
	v_lshlrev_b32_e32 v6, 16, v18
	v_sqrt_f32_e32 v4, v4
	v_add_f32_e32 v5, v128, v32
	v_mul_f32_e32 v5, 0xbfb8aa3b, v5
	v_exp_f32_e32 v5, v5
	v_mul_f32_e32 v2, v2, v4
	v_add_f32_e32 v4, v129, v16
	v_mul_f32_e32 v4, 0xbfb8aa3b, v4
	v_add_f32_e32 v3, 1.0, v5
	v_rcp_f32_e64 v3, -v3
	v_exp_f32_e32 v4, v4
	v_mul_f32_e32 v2, v2, v6
	ds_write_b32 v161, v2
	v_mul_f32_e32 v3, v130, v3
	v_add_f32_e32 v2, 1.0, v4
	v_add_f32_e32 v4, v3, v3
	v_fmamk_f32 v5, v4, 0x3ab60b61, v218
	v_fmaak_f32 v5, v4, v5, 0x3d2aaaab
	v_fmaak_f32 v5, v4, v5, 0x3e2aaaab
	v_fma_f32 v5, v4, v5, 0.5
	v_fma_f32 v5, v4, v5, 1.0
	v_mul_f32_e64 v4, v5, -v4
	v_max_f32_e32 v4, 0, v4
	v_mul_f32_e32 v3, 0x3fb8aa3b, v3
	v_rcp_f32_e32 v2, v2
	v_exp_f32_e32 v3, v3
	ds_write_b32 v162, v3 offset:34816
	s_waitcnt lgkmcnt(14)
	v_lshlrev_b32_e32 v6, 16, v19
	v_sqrt_f32_e32 v4, v4
	v_add_f32_e32 v5, v128, v33
	v_mul_f32_e32 v5, 0xbfb8aa3b, v5
	v_exp_f32_e32 v5, v5
	v_mul_f32_e32 v2, v2, v4
	v_add_f32_e32 v4, v129, v17
	v_mul_f32_e32 v4, 0xbfb8aa3b, v4
	v_add_f32_e32 v3, 1.0, v5
	v_rcp_f32_e64 v3, -v3
	v_exp_f32_e32 v4, v4
	v_mul_f32_e32 v2, v2, v6
	ds_write_b32 v163, v2
	v_mul_f32_e32 v3, v130, v3
	v_add_f32_e32 v2, 1.0, v4
	v_add_f32_e32 v4, v3, v3
	v_fmamk_f32 v5, v4, 0x3ab60b61, v218
	v_fmaak_f32 v5, v4, v5, 0x3d2aaaab
	v_fmaak_f32 v5, v4, v5, 0x3e2aaaab
	v_fma_f32 v5, v4, v5, 0.5
	v_fma_f32 v5, v4, v5, 1.0
	v_mul_f32_e64 v4, v5, -v4
	v_max_f32_e32 v4, 0, v4
	v_rcp_f32_e32 v2, v2
	v_mul_f32_e32 v3, 0x3fb8aa3b, v3
	v_exp_f32_e32 v3, v3
	ds_write_b32 v164, v3 offset:34816
	s_nop 1
	v_sqrt_f32_e32 v4, v4
	s_waitcnt lgkmcnt(14)
	v_lshlrev_b32_e32 v5, 16, v20
	v_mul_f32_e32 v2, v2, v4
	v_mul_f32_e32 v2, v2, v5
	ds_write_b32 v165, v2
	s_waitcnt lgkmcnt(0)
	s_barrier
; __device__ __forceinline__ void rglru_unit(const Params& P, int l, int unit, LAS unsigned char* lds, bool dry = false) {
;     ...
;         { const int c = sc, s = ss;
;           float As = 1.f, Hs = 0.f;
; #pragma unroll
;           for (int k = 0; k < 16; ++k) { const float a = Ab[(16 * s + k) * 64 + c], u = Ub[(16 * s + k) * 64 + c]; Hs = a * Hs + u; As *= a; }
;           seg[s * 64 + c] = (f32x2){As, Hs};
;           __syncthreads();
	ds_read2st64_b32 v[2:3], v133 offset0:136 offset1:137
	ds_read2st64_b32 v[4:5], v133 offset0:138 offset1:139
	ds_read2st64_b32 v[6:7], v133 offset0:140 offset1:141
	ds_read2st64_b32 v[8:9], v133 offset0:142 offset1:143
	ds_read_b32 v10, v166
	ds_read_b32 v11, v167
	ds_read_b32 v12, v168
	ds_read_b32 v13, v169
	ds_read_b32 v14, v170
	ds_read_b32 v15, v171
	ds_read_b32 v16, v172
	ds_read_b32 v18, v173
	s_waitcnt lgkmcnt(7)
	v_fmac_f32_e32 v10, 0, v2
	s_waitcnt lgkmcnt(6)
	v_fmac_f32_e32 v11, v10, v3
	s_waitcnt lgkmcnt(5)
	v_fmac_f32_e32 v12, v11, v4
	s_waitcnt lgkmcnt(4)
	v_fmac_f32_e32 v13, v12, v5
	s_waitcnt lgkmcnt(3)
	v_fmac_f32_e32 v14, v13, v6
	s_waitcnt lgkmcnt(2)
	v_fmac_f32_e32 v15, v14, v7
	s_waitcnt lgkmcnt(1)
	v_fmac_f32_e32 v16, v15, v8
	v_mul_f32_e32 v2, v2, v3
	s_waitcnt lgkmcnt(0)
	v_fmac_f32_e32 v18, v16, v9
	ds_read2st64_b32 v[10:11], v133 offset0:144 offset1:145
	ds_read2st64_b32 v[12:13], v133 offset0:146 offset1:147
	ds_read2st64_b32 v[14:15], v133 offset0:148 offset1:149
	ds_read2st64_b32 v[16:17], v133 offset0:150 offset1:151
	ds_read_b32 v3, v174
	ds_read_b32 v19, v175
	ds_read_b32 v21, v176
	ds_read_b32 v23, v177
	ds_read_b32 v25, v178
	ds_read_b32 v27, v179
	ds_read_b32 v29, v186
	ds_read_b32 v31, v187
	s_waitcnt lgkmcnt(7)
	v_fmac_f32_e32 v3, v18, v10
	v_mov_b32_e32 v32, v4
	v_mov_b32_e32 v33, v11
	v_mov_b32_e32 v18, v5
	v_mul_f32_e32 v4, v2, v4
	s_waitcnt lgkmcnt(6)
	v_pk_fma_f32 v[2:3], v[2:3], v[32:33], v[18:19]
	v_mul_f32_e32 v4, v4, v5
	v_mov_b32_e32 v5, v3
	v_mov_b32_e32 v2, v6
	v_mov_b32_e32 v3, v12
	v_pk_mul_f32 v[18:19], v[4:5], v[2:3]
	v_mov_b32_e32 v6, v7
	v_mov_b32_e32 v20, v7
	v_pk_mul_f32 v[6:7], v[18:19], v[6:7]
	s_waitcnt lgkmcnt(5)
	v_pk_fma_f32 v[2:3], v[4:5], v[2:3], v[20:21]
	v_mov_b32_e32 v4, v8
	v_mov_b32_e32 v2, v6
	v_mov_b32_e32 v5, v13
	v_pk_mul_f32 v[6:7], v[6:7], v[8:9]
	v_mov_b32_e32 v8, v9
	v_mov_b32_e32 v22, v9
	v_pk_mul_f32 v[6:7], v[6:7], v[8:9]
	s_waitcnt lgkmcnt(4)
	v_pk_fma_f32 v[2:3], v[2:3], v[4:5], v[22:23]
	v_mov_b32_e32 v8, v11
	v_mov_b32_e32 v7, v3
	v_mov_b32_e32 v2, v10
	v_mov_b32_e32 v3, v14
	v_pk_mul_f32 v[4:5], v[6:7], v[2:3]
	v_mov_b32_e32 v24, v11
	v_pk_mul_f32 v[4:5], v[4:5], v[8:9]
	s_waitcnt lgkmcnt(3)
	v_pk_fma_f32 v[2:3], v[6:7], v[2:3], v[24:25]
	v_mov_b32_e32 v6, v12
	v_mov_b32_e32 v2, v4
	v_mov_b32_e32 v7, v15
	v_pk_mul_f32 v[4:5], v[4:5], v[12:13]
	v_mov_b32_e32 v8, v13
	v_mov_b32_e32 v26, v13
	v_pk_mul_f32 v[4:5], v[4:5], v[8:9]
	s_waitcnt lgkmcnt(2)
	v_pk_fma_f32 v[2:3], v[2:3], v[6:7], v[26:27]
	v_mov_b32_e32 v8, v15
	v_mov_b32_e32 v5, v3
	v_mov_b32_e32 v2, v14
	v_mov_b32_e32 v3, v16
	v_pk_mul_f32 v[6:7], v[4:5], v[2:3]
	v_mov_b32_e32 v28, v15
	v_pk_mul_f32 v[6:7], v[6:7], v[8:9]
	s_waitcnt lgkmcnt(1)
	v_pk_fma_f32 v[2:3], v[4:5], v[2:3], v[28:29]
	v_pk_mul_f32 v[4:5], v[6:7], v[16:17]
	v_mov_b32_e32 v2, v6
	v_mov_b32_e32 v6, v17
	v_mov_b32_e32 v30, v17
	v_pk_mul_f32 v[4:5], v[4:5], v[6:7]
	s_waitcnt lgkmcnt(0)
	v_pk_fma_f32 v[2:3], v[2:3], v[16:17], v[30:31]
	s_nop 0
	v_mov_b32_e32 v5, v3
	ds_write_b64 v131, v[4:5]
	s_waitcnt lgkmcnt(0)
	s_barrier
; __device__ __forceinline__ unsigned f2bf(float f) { unsigned u = __builtin_bit_cast(unsigned, f); return (u + 0x7fffu + ((u >> 16) & 1u)) >> 16; }
; __device__ __forceinline__ void rglru_unit(const Params& P, int l, int unit, LAS unsigned char* lds, bool dry = false) {
;     ...
;           float hin = carry, hn = carry;
; #pragma unroll
;           for (int s2 = 0; s2 < 8; ++s2) { if (s2 == s) hin = hn; const f32x2 sg = seg[s2 * 64 + c]; hn = sg.x * hn + sg.y; }
;           carry = hn;
;           float h = hin;
; #pragma unroll
;           for (int k = 0; k < 16; ++k) { const float a = Ab[(16 * s + k) * 64 + c], u = Ub[(16 * s + k) * 64 + c]; h = a * h + u;
;               const float gg = bf2f(gq[k]); gp[(size_t)k * XP] = (bf16_t)f2bf(dry ? gg : gg * h); }
	ds_read2st64_b64 v[2:5], v132 offset1:1
	ds_read2st64_b64 v[6:9], v132 offset0:2 offset1:3
	s_waitcnt lgkmcnt(1)
	v_fma_f32 v2, v89, v2, v3
	v_cndmask_b32_e64 v3, v89, v2, s[6:7]
	v_fmac_f32_e32 v5, v4, v2
	v_cndmask_b32_e64 v10, v3, v5, s[8:9]
	s_waitcnt lgkmcnt(0)
	v_fma_f32 v6, v6, v5, v7
	ds_read2st64_b64 v[2:5], v132 offset0:4 offset1:5
	ds_read2st64_b64 v[86:89], v132 offset0:6 offset1:7
	v_cndmask_b32_e64 v7, v10, v6, s[10:11]
	v_fmac_f32_e32 v9, v8, v6
	v_cndmask_b32_e64 v6, v7, v9, s[12:13]
	s_waitcnt lgkmcnt(1)
	v_fma_f32 v2, v2, v9, v3
	v_cndmask_b32_e64 v3, v6, v2, s[14:15]
	v_fmac_f32_e32 v5, v4, v2
	v_cndmask_b32_e64 v2, v3, v5, s[16:17]
	s_waitcnt lgkmcnt(0)
	v_fma_f32 v10, v86, v5, v87
	v_cndmask_b32_e64 v11, v2, v10, s[18:19]
	ds_read2st64_b32 v[2:3], v133 offset0:136 offset1:137
	ds_read2st64_b32 v[4:5], v133 offset0:138 offset1:139
	ds_read2st64_b32 v[6:7], v133 offset0:140 offset1:141
	ds_read2st64_b32 v[8:9], v133 offset0:142 offset1:143
	ds_read_b32 v12, v166
	ds_read_b32 v13, v167
	ds_read_b32 v14, v168
	ds_read_b32 v15, v169
	ds_read_b32 v16, v170
	ds_read_b32 v17, v171
	ds_read_b32 v18, v172
	ds_read_b32 v19, v173
	s_waitcnt lgkmcnt(7)
	v_fmac_f32_e32 v12, v2, v11
	s_waitcnt vmcnt(0)
	v_lshlrev_b32_e32 v1, 16, v1
	v_lshlrev_b32_e32 v2, 16, v207
	v_mul_f32_e32 v2, v12, v2
	v_bfe_u32 v11, v2, 16, 1
	v_add3_u32 v2, v2, v11, s60
	global_store_short_d16_hi v[126:127], v2, off
	s_waitcnt lgkmcnt(0)
	v_fmac_f32_e32 v13, v3, v12
	v_lshlrev_b32_e32 v2, 16, v206
	v_mul_f32_e32 v2, v13, v2
	v_bfe_u32 v3, v2, 16, 1
	v_add3_u32 v2, v2, v3, s60
	global_store_short_d16_hi v[126:127], v2, off offset:2048
	v_fmac_f32_e32 v14, v4, v13
	v_lshlrev_b32_e32 v2, 16, v205
	v_mul_f32_e32 v2, v14, v2
	v_bfe_u32 v3, v2, 16, 1
	v_add3_u32 v2, v2, v3, s60
	global_store_short_d16_hi v[124:125], v2, off
	v_fmac_f32_e32 v15, v5, v14
	v_lshlrev_b32_e32 v2, 16, v204
	v_mul_f32_e32 v2, v15, v2
	v_bfe_u32 v3, v2, 16, 1
	v_add3_u32 v2, v2, v3, s60
	global_store_short_d16_hi v[124:125], v2, off offset:2048
	v_fmac_f32_e32 v16, v6, v15
	v_lshlrev_b32_e32 v2, 16, v203
	v_mul_f32_e32 v2, v16, v2
	v_bfe_u32 v3, v2, 16, 1
	v_add3_u32 v2, v2, v3, s60
	global_store_short_d16_hi v[122:123], v2, off
	v_fmac_f32_e32 v17, v7, v16
	v_lshlrev_b32_e32 v2, 16, v202
	v_mul_f32_e32 v2, v17, v2
	v_bfe_u32 v3, v2, 16, 1
	v_add3_u32 v2, v2, v3, s60
	global_store_short_d16_hi v[122:123], v2, off offset:2048
	v_fmac_f32_e32 v18, v8, v17
	v_lshlrev_b32_e32 v2, 16, v201
	v_mul_f32_e32 v2, v18, v2
	v_bfe_u32 v3, v2, 16, 1
	v_add3_u32 v2, v2, v3, s60
	global_store_short_d16_hi v[120:121], v2, off
	v_fmac_f32_e32 v19, v9, v18
	v_lshlrev_b32_e32 v2, 16, v200
	v_mul_f32_e32 v2, v19, v2
	v_bfe_u32 v3, v2, 16, 1
	v_add3_u32 v2, v2, v3, s60
	global_store_short_d16_hi v[120:121], v2, off offset:2048
	ds_read2st64_b32 v[2:3], v133 offset0:144 offset1:145
	ds_read2st64_b32 v[4:5], v133 offset0:146 offset1:147
	ds_read2st64_b32 v[6:7], v133 offset0:148 offset1:149
	ds_read2st64_b32 v[8:9], v133 offset0:150 offset1:151
	ds_read_b32 v11, v174
	ds_read_b32 v12, v175
	ds_read_b32 v13, v176
	ds_read_b32 v14, v177
	ds_read_b32 v15, v178
	ds_read_b32 v16, v179
	ds_read_b32 v17, v186
	ds_read_b32 v18, v187
	s_waitcnt lgkmcnt(0)
	v_fmac_f32_e32 v11, v19, v2
	v_lshlrev_b32_e32 v2, 16, v199
	v_mul_f32_e32 v2, v11, v2
	v_bfe_u32 v19, v2, 16, 1
	v_add3_u32 v2, v2, v19, s60
	global_store_short_d16_hi v[118:119], v2, off
	v_fmac_f32_e32 v12, v11, v3
	v_lshlrev_b32_e32 v2, 16, v198
	v_mul_f32_e32 v2, v12, v2
	v_bfe_u32 v3, v2, 16, 1
	v_add3_u32 v2, v2, v3, s60
	global_store_short_d16_hi v[118:119], v2, off offset:2048
	v_fmac_f32_e32 v13, v12, v4
	v_lshlrev_b32_e32 v2, 16, v197
	v_mul_f32_e32 v2, v13, v2
	v_bfe_u32 v3, v2, 16, 1
	v_add3_u32 v2, v2, v3, s60
	global_store_short_d16_hi v[116:117], v2, off
	v_fmac_f32_e32 v14, v13, v5
	v_lshlrev_b32_e32 v2, 16, v196
	v_mul_f32_e32 v2, v14, v2
	v_bfe_u32 v3, v2, 16, 1
	v_add3_u32 v2, v2, v3, s60
	global_store_short_d16_hi v[116:117], v2, off offset:2048
	v_fmac_f32_e32 v15, v14, v6
	v_lshlrev_b32_e32 v2, 16, v195
	v_mul_f32_e32 v2, v15, v2
	v_bfe_u32 v3, v2, 16, 1
	v_add3_u32 v2, v2, v3, s60
	global_store_short_d16_hi v[114:115], v2, off
	v_fmac_f32_e32 v16, v15, v7
	v_lshlrev_b32_e32 v2, 16, v194
	v_mul_f32_e32 v2, v16, v2
	v_bfe_u32 v3, v2, 16, 1
	v_add3_u32 v2, v2, v3, s60
	global_store_short_d16_hi v[114:115], v2, off offset:2048
	v_fmac_f32_e32 v17, v16, v8
	v_lshlrev_b32_e32 v2, 16, v111
	v_mul_f32_e32 v2, v17, v2
	v_bfe_u32 v3, v2, 16, 1
	v_fmac_f32_e32 v18, v17, v9
	v_add3_u32 v2, v2, v3, s60
	v_mul_f32_e32 v1, v18, v1
	global_store_short_d16_hi v[112:113], v2, off
	v_bfe_u32 v2, v1, 16, 1
	v_add3_u32 v1, v1, v2, s60
	v_fmac_f32_e32 v89, v88, v10
	global_store_short_d16_hi v[112:113], v1, off offset:2048
	s_cbranch_scc0 .LBB0_346
